# barrier: last XCD leader releases all XCDs directly; first two HGRN2 items per workgroup static
# speedup vs baseline: 1.0851x; 1.0200x over previous
; __device__ __forceinline__ unsigned xb_ld(unsigned* p)              { return __hip_atomic_load(p, __ATOMIC_RELAXED, __HIP_MEMORY_SCOPE_AGENT); }
; __device__ __forceinline__ unsigned xb_add(unsigned* p, unsigned v) { return __hip_atomic_fetch_add(p, v, __ATOMIC_RELAXED, __HIP_MEMORY_SCOPE_AGENT); }
; #define XB_SPIN(cond, bar) do { unsigned _sp = 0; while (cond) { __builtin_amdgcn_s_sleep(1); \
;     if ((++_sp & 255u) == 0u) { if (xb_ld(&(bar)[XB_TMO])) break; if (_sp > XB_SPIN_CAP) { atomicAdd(&(bar)[XB_TMO], 1u); break; } } } } while (0)
; __device__ __forceinline__ void xcd_barrier(const XcdBarrier& b) {
;     ...
;         const unsigned old = xb_add(&bar[XB_XSUB(b.x)], 1u);
;         const unsigned gen = old / nloc;
;         if (old + 1u == (gen + 1u) * nloc) {
;             __builtin_amdgcn_fence(__ATOMIC_RELEASE, "agent");
;             asm volatile("s_waitcnt vmcnt(0)" ::: "memory");
;             const unsigned og = xb_add(&bar[XB_TOP], 1u);
;             const unsigned tg = og / nx;
;             if (og + 1u == (tg + 1u) * nx) xb_add(&bar[XB_TOPGEN], 1u);
;             else XB_SPIN(xb_ld(&bar[XB_TOPGEN]) == tg, bar);
;             __builtin_amdgcn_fence(__ATOMIC_ACQUIRE, "agent");
;             xb_add(&bar[XB_XGEN(b.x)], 1u);
;             asm volatile("s_waitcnt vmcnt(0)" ::: "memory");
;         } else {
;             XB_SPIN(xb_ld(&bar[XB_XGEN(b.x)]) == gen, bar);
.LBB0_1446:
	s_or_b64 exec, exec, s[6:7]
	s_waitcnt vmcnt(0)
	v_readfirstlane_b32 s4, v2
	v_cvt_f32_u32_e32 v2, v0
	v_sub_u32_e32 v3, 0, v0
	v_add_u32_e32 v1, s4, v1
	v_readlane_b32 s4, v253, 42
	v_rcp_iflag_f32_e32 v2, v2
	v_readlane_b32 s5, v253, 43
	s_mov_b64 s[6:7], -1
	v_mul_f32_e32 v2, 0x4f7ffffe, v2
	v_cvt_u32_f32_e32 v2, v2
	v_mul_lo_u32 v3, v3, v2
	v_mul_hi_u32 v3, v2, v3
	v_add_u32_e32 v2, v2, v3
	v_mul_hi_u32 v2, v1, v2
	v_mul_lo_u32 v3, v2, v0
	v_sub_u32_e32 v3, v1, v3
	v_cmp_ge_u32_e32 vcc, v3, v0
	v_add_u32_e32 v4, 1, v2
	v_add_u32_e32 v1, 1, v1
	v_cndmask_b32_e32 v2, v2, v4, vcc
	v_sub_u32_e32 v4, v3, v0
	v_cndmask_b32_e32 v3, v3, v4, vcc
	v_cmp_ge_u32_e32 vcc, v3, v0
	v_add_u32_e32 v3, 1, v2
	s_nop 0
	v_cndmask_b32_e32 v2, v2, v3, vcc
	v_mul_lo_u32 v3, v0, v2
	v_add_u32_e32 v0, v3, v0
	v_cmp_ne_u32_e32 vcc, v1, v0
	v_mov_b64_e32 v[0:1], s[4:5]
	s_and_saveexec_b64 s[4:5], vcc
	s_cbranch_execz .LBB0_1458
	s_add_u32 s6, s2, 0x2400
	s_addc_u32 s7, s3, 0
	s_mov_b64 s[8:9], 0
	s_nop 3
	global_load_dword v0, v193, s[6:7] sc1
	s_waitcnt vmcnt(0)
	v_cmp_eq_u32_e32 vcc, v0, v2
	s_and_saveexec_b64 s[6:7], vcc
	s_cbranch_execz .LBB0_1457
	s_mov_b32 s18, 1
	s_branch .LBB0_1450

; __device__ __forceinline__ unsigned xb_ld(unsigned* p)              { return __hip_atomic_load(p, __ATOMIC_RELAXED, __HIP_MEMORY_SCOPE_AGENT); }
; __device__ __forceinline__ unsigned xb_add(unsigned* p, unsigned v) { return __hip_atomic_fetch_add(p, v, __ATOMIC_RELAXED, __HIP_MEMORY_SCOPE_AGENT); }
; #define XB_SPIN(cond, bar) do { unsigned _sp = 0; while (cond) { __builtin_amdgcn_s_sleep(1); \
;     if ((++_sp & 255u) == 0u) { if (xb_ld(&(bar)[XB_TMO])) break; if (_sp > XB_SPIN_CAP) { atomicAdd(&(bar)[XB_TMO], 1u); break; } } } } while (0)
; __device__ __forceinline__ void xcd_barrier(const XcdBarrier& b) {
;     ...
;             const unsigned og = xb_add(&bar[XB_TOP], 1u);
;             const unsigned tg = og / nx;
;             if (og + 1u == (tg + 1u) * nx) xb_add(&bar[XB_TOPGEN], 1u);
;             else XB_SPIN(xb_ld(&bar[XB_TOPGEN]) == tg, bar);
;             __builtin_amdgcn_fence(__ATOMIC_ACQUIRE, "agent");
;             xb_add(&bar[XB_XGEN(b.x)], 1u);
;             asm volatile("s_waitcnt vmcnt(0)" ::: "memory");
;         } else {
;             XB_SPIN(xb_ld(&bar[XB_XGEN(b.x)]) == gen, bar);
.LBB0_1454:
	s_add_u32 s12, s2, 0x2400
	s_addc_u32 s13, s3, 0
	s_add_i32 s18, s18, 1
	s_mov_b64 s[14:15], -1
	s_nop 2
	global_load_dword v0, v193, s[12:13] sc1
	s_waitcnt vmcnt(0)
	v_cmp_ne_u32_e32 vcc, v0, v2
	s_orn2_b64 s[12:13], vcc, exec
	s_branch .LBB0_1449

; __device__ __forceinline__ unsigned xb_ld(unsigned* p)              { return __hip_atomic_load(p, __ATOMIC_RELAXED, __HIP_MEMORY_SCOPE_AGENT); }
; __device__ __forceinline__ unsigned xb_add(unsigned* p, unsigned v) { return __hip_atomic_fetch_add(p, v, __ATOMIC_RELAXED, __HIP_MEMORY_SCOPE_AGENT); }
; #define XB_SPIN(cond, bar) do { unsigned _sp = 0; while (cond) { __builtin_amdgcn_s_sleep(1); \
;     if ((++_sp & 255u) == 0u) { if (xb_ld(&(bar)[XB_TMO])) break; if (_sp > XB_SPIN_CAP) { atomicAdd(&(bar)[XB_TMO], 1u); break; } } } } while (0)
; __device__ __forceinline__ void xcd_barrier(const XcdBarrier& b) {
;     ...
;             const unsigned og = xb_add(&bar[XB_TOP], 1u);
;             const unsigned tg = og / nx;
;             if (og + 1u == (tg + 1u) * nx) xb_add(&bar[XB_TOPGEN], 1u);
;             else XB_SPIN(xb_ld(&bar[XB_TOPGEN]) == tg, bar);
;             __builtin_amdgcn_fence(__ATOMIC_ACQUIRE, "agent");
;             xb_add(&bar[XB_XGEN(b.x)], 1u);
;             asm volatile("s_waitcnt vmcnt(0)" ::: "memory");
.LBB0_1458:
	s_or_b64 exec, exec, s[4:5]
	s_and_saveexec_b64 s[4:5], s[6:7]
	s_cbranch_execz .LBB0_1460
	v_mov_b32_e32 v2, 1
	global_atomic_add v[0:1], v2, off
	v_readlane_b32 s98, v253, 0
	v_readlane_b32 s99, v253, 1
	v_mov_b32_e32 v3, 0x2400
	s_nop 4
	global_atomic_add v3, v2, s[98:99]
	global_atomic_add v3, v2, s[98:99] offset:256
	global_atomic_add v3, v2, s[98:99] offset:512
	global_atomic_add v3, v2, s[98:99] offset:768
	global_atomic_add v3, v2, s[98:99] offset:1024
	global_atomic_add v3, v2, s[98:99] offset:1280
	global_atomic_add v3, v2, s[98:99] offset:1536
	global_atomic_add v3, v2, s[98:99] offset:1792
	global_atomic_add v3, v2, s[98:99] offset:2048
	global_atomic_add v3, v2, s[98:99] offset:2304
	global_atomic_add v3, v2, s[98:99] offset:2560
	global_atomic_add v3, v2, s[98:99] offset:2816
	global_atomic_add v3, v2, s[98:99] offset:3072
	global_atomic_add v3, v2, s[98:99] offset:3328
	global_atomic_add v3, v2, s[98:99] offset:3584
	global_atomic_add v3, v2, s[98:99] offset:3840
.LBB0_1460:
	s_or_b64 exec, exec, s[4:5]
	s_mov_b64 s[4:5], exec
	v_mbcnt_lo_u32_b32 v0, s4, 0
	v_mbcnt_hi_u32_b32 v0, s5, v0
	v_cmp_eq_u32_e32 vcc, 0, v0
	s_waitcnt vmcnt(0)
	s_and_saveexec_b64 s[6:7], vcc
	s_cbranch_execz .LBB0_1462
	s_bcnt1_i32_b64 s4, s[4:5]
	v_mov_b32_e32 v0, s4
	v_mov_b32_e32 v1, 0x2000
.LBB0_1462:
	s_or_b64 exec, exec, s[6:7]
	s_waitcnt vmcnt(0)

; #define LAS __attribute__((address_space(3)))
; __global__ void __launch_bounds__(512, 2) mega_fwd(Args args) {
;     ...
;                 volatile LAS unsigned* LW = (volatile LAS unsigned*)(lds + LDS_BARST);
;                 unsigned* ctr = (unsigned*)(w_ + WS_CTR) + 2 * l_;
;                 unsigned nextq = 0; int cur;
;                 if (ph == 0) { if (tid == 0) LW[4] = atomicAdd(ctr, 1u); __syncthreads(); cur = (int)LW[4]; if (tid == 0) nextq = atomicAdd(ctr, 1u); }
;                 else cur = bid;
.LBB0_1471:
	s_or_b64 exec, exec, s[4:5]
	v_mov_b32_e32 v2, s8
	v_readlane_b32 s0, v254, 23
	s_nop 1
	v_mov_b32_e32 v3, s0
	ds_write_b32 v3, v2

; __global__ void __launch_bounds__(512, 2) mega_fwd(Args args) {
;     ...
;                 if (ph == 0) { if (tid == 0) LW[4] = atomicAdd(ctr, 1u); __syncthreads(); cur = (int)LW[4]; if (tid == 0) nextq = atomicAdd(ctr, 1u); }
.LBB0_1475:
	s_or_b64 exec, exec, s[2:3]
	s_add_i32 s2, s8, 0x100
	v_mov_b32_e32 v75, s2

; __global__ void __launch_bounds__(512, 2) mega_fwd(Args args) {
;     ...
;                     if (ph == 0) { __syncthreads(); if (tid == 0) LW[4] = nextq; __syncthreads(); nxt = (int)LW[4]; if (tid == 0 && nxt < nit) nextq = atomicAdd(ctr, 1u); }
.LBB0_1489:
	s_or_b64 exec, exec, s[4:5]
	s_waitcnt vmcnt(0)
	v_readfirstlane_b32 s0, v1
	s_addk_i32 s0, 0x200
	s_nop 1
	v_add_u32_e32 v75, s0, v0

; __device__ __forceinline__ unsigned xb_add(unsigned* p, unsigned v) { return __hip_atomic_fetch_add(p, v, __ATOMIC_RELAXED, __HIP_MEMORY_SCOPE_AGENT); }
; __device__ __forceinline__ void xcd_barrier(const XcdBarrier& b) {
;     ...
;             __builtin_amdgcn_fence(__ATOMIC_ACQUIRE, "agent");
;             xb_add(&bar[XB_XGEN(b.x)], 1u);
;             asm volatile("s_waitcnt vmcnt(0)" ::: "memory");
.LBB0_1761:
	s_or_b64 exec, exec, s[4:5]
	s_mov_b64 s[4:5], exec
	v_mbcnt_lo_u32_b32 v0, s4, 0
	v_mbcnt_hi_u32_b32 v0, s5, v0
	v_cmp_eq_u32_e32 vcc, 0, v0
	s_waitcnt vmcnt(0)
	s_and_saveexec_b64 s[6:7], vcc
	s_cbranch_execz .LBB0_1464
	s_bcnt1_i32_b64 s4, s[4:5]
	v_mov_b32_e32 v0, s4
	v_mov_b32_e32 v1, 0x2000
	s_branch .LBB0_1464

; __device__ __forceinline__ unsigned xb_ld(unsigned* p)              { return __hip_atomic_load(p, __ATOMIC_RELAXED, __HIP_MEMORY_SCOPE_AGENT); }
; __device__ __forceinline__ unsigned xb_add(unsigned* p, unsigned v) { return __hip_atomic_fetch_add(p, v, __ATOMIC_RELAXED, __HIP_MEMORY_SCOPE_AGENT); }
; #define XB_SPIN(cond, bar) do { unsigned _sp = 0; while (cond) { __builtin_amdgcn_s_sleep(1); \
;     if ((++_sp & 255u) == 0u) { if (xb_ld(&(bar)[XB_TMO])) break; if (_sp > XB_SPIN_CAP) { atomicAdd(&(bar)[XB_TMO], 1u); break; } } } } while (0)
; __device__ __forceinline__ void xcd_barrier(const XcdBarrier& b) {
;     ...
;         const unsigned old = xb_add(&bar[XB_XSUB(b.x)], 1u);
;         const unsigned gen = old / nloc;
;         if (old + 1u == (gen + 1u) * nloc) {
;             __builtin_amdgcn_fence(__ATOMIC_RELEASE, "agent");
;             asm volatile("s_waitcnt vmcnt(0)" ::: "memory");
;             const unsigned og = xb_add(&bar[XB_TOP], 1u);
;             const unsigned tg = og / nx;
;             if (og + 1u == (tg + 1u) * nx) xb_add(&bar[XB_TOPGEN], 1u);
;             else XB_SPIN(xb_ld(&bar[XB_TOPGEN]) == tg, bar);
;             __builtin_amdgcn_fence(__ATOMIC_ACQUIRE, "agent");
;             xb_add(&bar[XB_XGEN(b.x)], 1u);
;             asm volatile("s_waitcnt vmcnt(0)" ::: "memory");
;         } else {
;             XB_SPIN(xb_ld(&bar[XB_XGEN(b.x)]) == gen, bar);
.LBB0_1898:
	s_or_b64 exec, exec, s[8:9]
	s_waitcnt vmcnt(0)
	v_readfirstlane_b32 s6, v2
	v_cvt_f32_u32_e32 v2, v0
	v_sub_u32_e32 v3, 0, v0
	v_add_u32_e32 v1, s6, v1
	v_readlane_b32 s6, v253, 42
	v_rcp_iflag_f32_e32 v2, v2
	v_readlane_b32 s7, v253, 43
	s_mov_b64 s[8:9], -1
	v_mul_f32_e32 v2, 0x4f7ffffe, v2
	v_cvt_u32_f32_e32 v2, v2
	v_mul_lo_u32 v3, v3, v2
	v_mul_hi_u32 v3, v2, v3
	v_add_u32_e32 v2, v2, v3
	v_mul_hi_u32 v2, v1, v2
	v_mul_lo_u32 v3, v2, v0
	v_sub_u32_e32 v3, v1, v3
	v_cmp_ge_u32_e32 vcc, v3, v0
	v_add_u32_e32 v4, 1, v2
	v_add_u32_e32 v1, 1, v1
	v_cndmask_b32_e32 v2, v2, v4, vcc
	v_sub_u32_e32 v4, v3, v0
	v_cndmask_b32_e32 v3, v3, v4, vcc
	v_cmp_ge_u32_e32 vcc, v3, v0
	v_add_u32_e32 v3, 1, v2
	s_nop 0
	v_cndmask_b32_e32 v2, v2, v3, vcc
	v_mul_lo_u32 v3, v0, v2
	v_add_u32_e32 v0, v3, v0
	v_cmp_ne_u32_e32 vcc, v1, v0
	v_mov_b64_e32 v[0:1], s[6:7]
	s_and_saveexec_b64 s[6:7], vcc
	s_cbranch_execz .LBB0_1910
	s_add_u32 s8, s4, 0x2400
	s_addc_u32 s9, s5, 0
	s_mov_b64 s[10:11], 0
	s_nop 3
	global_load_dword v0, v193, s[8:9] sc1
	s_waitcnt vmcnt(0)
	v_cmp_eq_u32_e32 vcc, v0, v2
	s_and_saveexec_b64 s[8:9], vcc
	s_cbranch_execz .LBB0_1909
	s_mov_b32 s30, 1
	s_branch .LBB0_1902

; __device__ __forceinline__ unsigned xb_ld(unsigned* p)              { return __hip_atomic_load(p, __ATOMIC_RELAXED, __HIP_MEMORY_SCOPE_AGENT); }
; __device__ __forceinline__ unsigned xb_add(unsigned* p, unsigned v) { return __hip_atomic_fetch_add(p, v, __ATOMIC_RELAXED, __HIP_MEMORY_SCOPE_AGENT); }
; #define XB_SPIN(cond, bar) do { unsigned _sp = 0; while (cond) { __builtin_amdgcn_s_sleep(1); \
;     if ((++_sp & 255u) == 0u) { if (xb_ld(&(bar)[XB_TMO])) break; if (_sp > XB_SPIN_CAP) { atomicAdd(&(bar)[XB_TMO], 1u); break; } } } } while (0)
; __device__ __forceinline__ void xcd_barrier(const XcdBarrier& b) {
;     ...
;             const unsigned og = xb_add(&bar[XB_TOP], 1u);
;             const unsigned tg = og / nx;
;             if (og + 1u == (tg + 1u) * nx) xb_add(&bar[XB_TOPGEN], 1u);
;             else XB_SPIN(xb_ld(&bar[XB_TOPGEN]) == tg, bar);
;             __builtin_amdgcn_fence(__ATOMIC_ACQUIRE, "agent");
;             xb_add(&bar[XB_XGEN(b.x)], 1u);
;             asm volatile("s_waitcnt vmcnt(0)" ::: "memory");
;         } else {
;             XB_SPIN(xb_ld(&bar[XB_XGEN(b.x)]) == gen, bar);
.LBB0_1906:
	s_add_u32 s24, s4, 0x2400
	s_addc_u32 s25, s5, 0
	s_add_i32 s30, s30, 1
	s_mov_b64 s[26:27], -1
	s_nop 2
	global_load_dword v0, v193, s[24:25] sc1
	s_waitcnt vmcnt(0)
	v_cmp_ne_u32_e32 vcc, v0, v2
	s_orn2_b64 s[24:25], vcc, exec
	s_branch .LBB0_1901

; __device__ __forceinline__ unsigned xb_ld(unsigned* p)              { return __hip_atomic_load(p, __ATOMIC_RELAXED, __HIP_MEMORY_SCOPE_AGENT); }
; __device__ __forceinline__ unsigned xb_add(unsigned* p, unsigned v) { return __hip_atomic_fetch_add(p, v, __ATOMIC_RELAXED, __HIP_MEMORY_SCOPE_AGENT); }
; #define XB_SPIN(cond, bar) do { unsigned _sp = 0; while (cond) { __builtin_amdgcn_s_sleep(1); \
;     if ((++_sp & 255u) == 0u) { if (xb_ld(&(bar)[XB_TMO])) break; if (_sp > XB_SPIN_CAP) { atomicAdd(&(bar)[XB_TMO], 1u); break; } } } } while (0)
; __device__ __forceinline__ void xcd_barrier(const XcdBarrier& b) {
;     ...
;             const unsigned og = xb_add(&bar[XB_TOP], 1u);
;             const unsigned tg = og / nx;
;             if (og + 1u == (tg + 1u) * nx) xb_add(&bar[XB_TOPGEN], 1u);
;             else XB_SPIN(xb_ld(&bar[XB_TOPGEN]) == tg, bar);
;             __builtin_amdgcn_fence(__ATOMIC_ACQUIRE, "agent");
;             xb_add(&bar[XB_XGEN(b.x)], 1u);
;             asm volatile("s_waitcnt vmcnt(0)" ::: "memory");
.LBB0_1910:
	s_or_b64 exec, exec, s[6:7]
	s_and_saveexec_b64 s[6:7], s[8:9]
	s_cbranch_execz .LBB0_1912
	v_mov_b32_e32 v2, 1
	global_atomic_add v[0:1], v2, off
	v_readlane_b32 s98, v253, 0
	v_readlane_b32 s99, v253, 1
	v_mov_b32_e32 v3, 0x2400
	s_nop 4
	global_atomic_add v3, v2, s[98:99]
	global_atomic_add v3, v2, s[98:99] offset:256
	global_atomic_add v3, v2, s[98:99] offset:512
	global_atomic_add v3, v2, s[98:99] offset:768
	global_atomic_add v3, v2, s[98:99] offset:1024
	global_atomic_add v3, v2, s[98:99] offset:1280
	global_atomic_add v3, v2, s[98:99] offset:1536
	global_atomic_add v3, v2, s[98:99] offset:1792
	global_atomic_add v3, v2, s[98:99] offset:2048
	global_atomic_add v3, v2, s[98:99] offset:2304
	global_atomic_add v3, v2, s[98:99] offset:2560
	global_atomic_add v3, v2, s[98:99] offset:2816
	global_atomic_add v3, v2, s[98:99] offset:3072
	global_atomic_add v3, v2, s[98:99] offset:3328
	global_atomic_add v3, v2, s[98:99] offset:3584
	global_atomic_add v3, v2, s[98:99] offset:3840
.LBB0_1912:
	s_or_b64 exec, exec, s[6:7]
	s_mov_b64 s[6:7], exec
	v_mbcnt_lo_u32_b32 v0, s6, 0
	v_mbcnt_hi_u32_b32 v0, s7, v0
	v_cmp_eq_u32_e32 vcc, 0, v0
	s_waitcnt vmcnt(0)
	s_and_saveexec_b64 s[8:9], vcc
	s_cbranch_execz .LBB0_1914
	s_bcnt1_i32_b64 s6, s[6:7]
	v_mov_b32_e32 v0, s6
	v_mov_b32_e32 v1, 0x2000
.LBB0_1914:
	s_or_b64 exec, exec, s[8:9]
	s_waitcnt vmcnt(0)

; __device__ __forceinline__ unsigned xb_ld(unsigned* p)              { return __hip_atomic_load(p, __ATOMIC_RELAXED, __HIP_MEMORY_SCOPE_AGENT); }
; __device__ __forceinline__ unsigned xb_add(unsigned* p, unsigned v) { return __hip_atomic_fetch_add(p, v, __ATOMIC_RELAXED, __HIP_MEMORY_SCOPE_AGENT); }
; #define XB_SPIN(cond, bar) do { unsigned _sp = 0; while (cond) { __builtin_amdgcn_s_sleep(1); \
;     if ((++_sp & 255u) == 0u) { if (xb_ld(&(bar)[XB_TMO])) break; if (_sp > XB_SPIN_CAP) { atomicAdd(&(bar)[XB_TMO], 1u); break; } } } } while (0)
; __device__ __forceinline__ void xcd_barrier(const XcdBarrier& b) {
;     ...
;         const unsigned old = xb_add(&bar[XB_XSUB(b.x)], 1u);
;         const unsigned gen = old / nloc;
;         if (old + 1u == (gen + 1u) * nloc) {
;             __builtin_amdgcn_fence(__ATOMIC_RELEASE, "agent");
;             asm volatile("s_waitcnt vmcnt(0)" ::: "memory");
;             const unsigned og = xb_add(&bar[XB_TOP], 1u);
;             const unsigned tg = og / nx;
;             if (og + 1u == (tg + 1u) * nx) xb_add(&bar[XB_TOPGEN], 1u);
;             else XB_SPIN(xb_ld(&bar[XB_TOPGEN]) == tg, bar);
;             __builtin_amdgcn_fence(__ATOMIC_ACQUIRE, "agent");
;             xb_add(&bar[XB_XGEN(b.x)], 1u);
;             asm volatile("s_waitcnt vmcnt(0)" ::: "memory");
;         } else {
;             XB_SPIN(xb_ld(&bar[XB_XGEN(b.x)]) == gen, bar);
.LBB0_1997:
	s_or_b64 exec, exec, s[6:7]
	s_waitcnt vmcnt(0)
	v_readfirstlane_b32 s4, v2
	v_cvt_f32_u32_e32 v2, v0
	v_sub_u32_e32 v3, 0, v0
	v_add_u32_e32 v1, s4, v1
	v_readlane_b32 s4, v253, 42
	v_rcp_iflag_f32_e32 v2, v2
	v_readlane_b32 s5, v253, 43
	s_mov_b64 s[6:7], -1
	v_mul_f32_e32 v2, 0x4f7ffffe, v2
	v_cvt_u32_f32_e32 v2, v2
	v_mul_lo_u32 v3, v3, v2
	v_mul_hi_u32 v3, v2, v3
	v_add_u32_e32 v2, v2, v3
	v_mul_hi_u32 v2, v1, v2
	v_mul_lo_u32 v3, v2, v0
	v_sub_u32_e32 v3, v1, v3
	v_cmp_ge_u32_e32 vcc, v3, v0
	v_add_u32_e32 v4, 1, v2
	v_add_u32_e32 v1, 1, v1
	v_cndmask_b32_e32 v2, v2, v4, vcc
	v_sub_u32_e32 v4, v3, v0
	v_cndmask_b32_e32 v3, v3, v4, vcc
	v_cmp_ge_u32_e32 vcc, v3, v0
	v_add_u32_e32 v3, 1, v2
	s_nop 0
	v_cndmask_b32_e32 v2, v2, v3, vcc
	v_mul_lo_u32 v3, v0, v2
	v_add_u32_e32 v0, v3, v0
	v_cmp_ne_u32_e32 vcc, v1, v0
	v_mov_b64_e32 v[0:1], s[4:5]
	s_and_saveexec_b64 s[4:5], vcc
	s_cbranch_execz .LBB0_2009
	s_add_u32 s6, s2, 0x2400
	s_addc_u32 s7, s3, 0
	s_mov_b64 s[8:9], 0
	s_nop 3
	global_load_dword v0, v193, s[6:7] sc1
	s_waitcnt vmcnt(0)
	v_cmp_eq_u32_e32 vcc, v0, v2
	s_and_saveexec_b64 s[6:7], vcc
	s_cbranch_execz .LBB0_2008
	s_mov_b32 s24, 1
	s_branch .LBB0_2001

; __device__ __forceinline__ unsigned xb_ld(unsigned* p)              { return __hip_atomic_load(p, __ATOMIC_RELAXED, __HIP_MEMORY_SCOPE_AGENT); }
; __device__ __forceinline__ unsigned xb_add(unsigned* p, unsigned v) { return __hip_atomic_fetch_add(p, v, __ATOMIC_RELAXED, __HIP_MEMORY_SCOPE_AGENT); }
; #define XB_SPIN(cond, bar) do { unsigned _sp = 0; while (cond) { __builtin_amdgcn_s_sleep(1); \
;     if ((++_sp & 255u) == 0u) { if (xb_ld(&(bar)[XB_TMO])) break; if (_sp > XB_SPIN_CAP) { atomicAdd(&(bar)[XB_TMO], 1u); break; } } } } while (0)
; __device__ __forceinline__ void xcd_barrier(const XcdBarrier& b) {
;     ...
;             const unsigned og = xb_add(&bar[XB_TOP], 1u);
;             const unsigned tg = og / nx;
;             if (og + 1u == (tg + 1u) * nx) xb_add(&bar[XB_TOPGEN], 1u);
;             else XB_SPIN(xb_ld(&bar[XB_TOPGEN]) == tg, bar);
;             __builtin_amdgcn_fence(__ATOMIC_ACQUIRE, "agent");
;             xb_add(&bar[XB_XGEN(b.x)], 1u);
;             asm volatile("s_waitcnt vmcnt(0)" ::: "memory");
;         } else {
;             XB_SPIN(xb_ld(&bar[XB_XGEN(b.x)]) == gen, bar);
.LBB0_2005:
	s_add_u32 s12, s2, 0x2400
	s_addc_u32 s13, s3, 0
	s_add_i32 s24, s24, 1
	s_mov_b64 s[20:21], -1
	s_nop 2
	global_load_dword v0, v193, s[12:13] sc1
	s_waitcnt vmcnt(0)
	v_cmp_ne_u32_e32 vcc, v0, v2
	s_orn2_b64 s[12:13], vcc, exec
	s_branch .LBB0_2000

; __device__ __forceinline__ unsigned xb_add(unsigned* p, unsigned v) { return __hip_atomic_fetch_add(p, v, __ATOMIC_RELAXED, __HIP_MEMORY_SCOPE_AGENT); }
; __device__ __forceinline__ void xcd_barrier(const XcdBarrier& b) {
;     ...
;             __builtin_amdgcn_fence(__ATOMIC_ACQUIRE, "agent");
;             xb_add(&bar[XB_XGEN(b.x)], 1u);
;             asm volatile("s_waitcnt vmcnt(0)" ::: "memory");
.LBB0_2011:
	s_or_b64 exec, exec, s[4:5]
	s_mov_b64 s[4:5], exec
	v_mbcnt_lo_u32_b32 v0, s4, 0
	v_mbcnt_hi_u32_b32 v0, s5, v0
	v_cmp_eq_u32_e32 vcc, 0, v0
	s_waitcnt vmcnt(0)
	s_and_saveexec_b64 s[6:7], vcc
	s_cbranch_execz .LBB0_2013
	s_bcnt1_i32_b64 s4, s[4:5]
	v_mov_b32_e32 v0, s4
	v_mov_b32_e32 v1, 0x2000
.LBB0_2013:
	s_or_b64 exec, exec, s[6:7]
	s_waitcnt vmcnt(0)

; __device__ __forceinline__ unsigned xb_ld(unsigned* p)              { return __hip_atomic_load(p, __ATOMIC_RELAXED, __HIP_MEMORY_SCOPE_AGENT); }
; __device__ __forceinline__ unsigned xb_add(unsigned* p, unsigned v) { return __hip_atomic_fetch_add(p, v, __ATOMIC_RELAXED, __HIP_MEMORY_SCOPE_AGENT); }
; #define XB_SPIN(cond, bar) do { unsigned _sp = 0; while (cond) { __builtin_amdgcn_s_sleep(1); \
;     if ((++_sp & 255u) == 0u) { if (xb_ld(&(bar)[XB_TMO])) break; if (_sp > XB_SPIN_CAP) { atomicAdd(&(bar)[XB_TMO], 1u); break; } } } } while (0)
; __device__ __forceinline__ void xcd_barrier(const XcdBarrier& b) {
;     ...
;         const unsigned old = xb_add(&bar[XB_XSUB(b.x)], 1u);
;         const unsigned gen = old / nloc;
;         if (old + 1u == (gen + 1u) * nloc) {
;             __builtin_amdgcn_fence(__ATOMIC_RELEASE, "agent");
;             asm volatile("s_waitcnt vmcnt(0)" ::: "memory");
;             const unsigned og = xb_add(&bar[XB_TOP], 1u);
;             const unsigned tg = og / nx;
;             if (og + 1u == (tg + 1u) * nx) xb_add(&bar[XB_TOPGEN], 1u);
;             else XB_SPIN(xb_ld(&bar[XB_TOPGEN]) == tg, bar);
;             __builtin_amdgcn_fence(__ATOMIC_ACQUIRE, "agent");
;             xb_add(&bar[XB_XGEN(b.x)], 1u);
;             asm volatile("s_waitcnt vmcnt(0)" ::: "memory");
;         } else {
;             XB_SPIN(xb_ld(&bar[XB_XGEN(b.x)]) == gen, bar);
.LBB0_2141:
	s_or_b64 exec, exec, s[6:7]
	s_waitcnt vmcnt(0)
	v_readfirstlane_b32 s4, v2
	v_cvt_f32_u32_e32 v2, v0
	v_sub_u32_e32 v3, 0, v0
	v_add_u32_e32 v1, s4, v1
	v_readlane_b32 s4, v253, 42
	v_rcp_iflag_f32_e32 v2, v2
	v_readlane_b32 s5, v253, 43
	s_mov_b64 s[6:7], -1
	v_mul_f32_e32 v2, 0x4f7ffffe, v2
	v_cvt_u32_f32_e32 v2, v2
	v_mul_lo_u32 v3, v3, v2
	v_mul_hi_u32 v3, v2, v3
	v_add_u32_e32 v2, v2, v3
	v_mul_hi_u32 v2, v1, v2
	v_mul_lo_u32 v3, v2, v0
	v_sub_u32_e32 v3, v1, v3
	v_cmp_ge_u32_e32 vcc, v3, v0
	v_add_u32_e32 v4, 1, v2
	v_add_u32_e32 v1, 1, v1
	v_cndmask_b32_e32 v2, v2, v4, vcc
	v_sub_u32_e32 v4, v3, v0
	v_cndmask_b32_e32 v3, v3, v4, vcc
	v_cmp_ge_u32_e32 vcc, v3, v0
	v_add_u32_e32 v3, 1, v2
	s_nop 0
	v_cndmask_b32_e32 v2, v2, v3, vcc
	v_mul_lo_u32 v3, v0, v2
	v_add_u32_e32 v0, v3, v0
	v_cmp_ne_u32_e32 vcc, v1, v0
	v_mov_b64_e32 v[0:1], s[4:5]
	s_and_saveexec_b64 s[4:5], vcc
	s_cbranch_execz .LBB0_2153
	s_add_u32 s6, s2, 0x2400
	s_addc_u32 s7, s3, 0
	s_mov_b64 s[8:9], 0
	s_nop 3
	global_load_dword v0, v193, s[6:7] sc1
	s_waitcnt vmcnt(0)
	v_cmp_eq_u32_e32 vcc, v0, v2
	s_and_saveexec_b64 s[6:7], vcc
	s_cbranch_execz .LBB0_2152
	s_mov_b32 s20, 1
	s_branch .LBB0_2145

; __device__ __forceinline__ unsigned xb_ld(unsigned* p)              { return __hip_atomic_load(p, __ATOMIC_RELAXED, __HIP_MEMORY_SCOPE_AGENT); }
; __device__ __forceinline__ unsigned xb_add(unsigned* p, unsigned v) { return __hip_atomic_fetch_add(p, v, __ATOMIC_RELAXED, __HIP_MEMORY_SCOPE_AGENT); }
; #define XB_SPIN(cond, bar) do { unsigned _sp = 0; while (cond) { __builtin_amdgcn_s_sleep(1); \
;     if ((++_sp & 255u) == 0u) { if (xb_ld(&(bar)[XB_TMO])) break; if (_sp > XB_SPIN_CAP) { atomicAdd(&(bar)[XB_TMO], 1u); break; } } } } while (0)
; __device__ __forceinline__ void xcd_barrier(const XcdBarrier& b) {
;     ...
;             const unsigned og = xb_add(&bar[XB_TOP], 1u);
;             const unsigned tg = og / nx;
;             if (og + 1u == (tg + 1u) * nx) xb_add(&bar[XB_TOPGEN], 1u);
;             else XB_SPIN(xb_ld(&bar[XB_TOPGEN]) == tg, bar);
;             __builtin_amdgcn_fence(__ATOMIC_ACQUIRE, "agent");
;             xb_add(&bar[XB_XGEN(b.x)], 1u);
;             asm volatile("s_waitcnt vmcnt(0)" ::: "memory");
;         } else {
;             XB_SPIN(xb_ld(&bar[XB_XGEN(b.x)]) == gen, bar);
.LBB0_2149:
	s_add_u32 s12, s2, 0x2400
	s_addc_u32 s13, s3, 0
	s_add_i32 s20, s20, 1
	s_mov_b64 s[16:17], -1
	s_nop 2
	global_load_dword v0, v193, s[12:13] sc1
	s_waitcnt vmcnt(0)
	v_cmp_ne_u32_e32 vcc, v0, v2
	s_orn2_b64 s[12:13], vcc, exec
	s_branch .LBB0_2144

; __device__ __forceinline__ unsigned xb_add(unsigned* p, unsigned v) { return __hip_atomic_fetch_add(p, v, __ATOMIC_RELAXED, __HIP_MEMORY_SCOPE_AGENT); }
; __device__ __forceinline__ void xcd_barrier(const XcdBarrier& b) {
;     ...
;             __builtin_amdgcn_fence(__ATOMIC_ACQUIRE, "agent");
;             xb_add(&bar[XB_XGEN(b.x)], 1u);
;             asm volatile("s_waitcnt vmcnt(0)" ::: "memory");
.LBB0_2155:
	s_or_b64 exec, exec, s[4:5]
	s_mov_b64 s[4:5], exec
	v_mbcnt_lo_u32_b32 v0, s4, 0
	v_mbcnt_hi_u32_b32 v0, s5, v0
	v_cmp_eq_u32_e32 vcc, 0, v0
	s_waitcnt vmcnt(0)
	s_and_saveexec_b64 s[6:7], vcc
	s_cbranch_execz .LBB0_2157
	s_bcnt1_i32_b64 s4, s[4:5]
	v_mov_b32_e32 v0, s4
	v_mov_b32_e32 v1, 0x2000
.LBB0_2157:
	s_or_b64 exec, exec, s[6:7]
	s_waitcnt vmcnt(0)
